# v8: v7 + sample-chain scan loop: current-chunk loads issued before next-chunk prefetch, counted mid-step waits, prefetch drained at loop bottom
# speedup vs baseline: 1.0029x; 1.0029x over previous
.LBB0_836:
	s_ashr_i32 s4, s15, 3
	s_or_b32 s4, s4, s10
	s_ashr_i32 s5, s4, 31
	s_lshl_b64 s[4:5], s[4:5], 7
	v_lshl_add_u64 v[72:73], v[142:143], 0, s[4:5]
	v_lshlrev_b64 v[72:73], 7, v[72:73]
	v_lshl_add_u64 v[76:77], v[148:149], 0, v[72:73]
	v_lshl_add_u64 v[72:73], v[130:131], 0, s[4:5]
	v_lshlrev_b64 v[72:73], 7, v[72:73]
	v_lshl_add_u64 v[78:79], v[150:151], 0, v[72:73]
	global_load_dwordx4 v[124:127], v[76:77], off
	global_load_dwordx4 v[80:83], v[78:79], off
	global_load_dwordx4 v[72:75], v[78:79], off offset:2048
	global_load_dwordx4 v[116:119], v[76:77], off offset:64
	global_load_dwordx4 v[84:87], v[78:79], off offset:64
	s_nop 0
	global_load_dwordx4 v[76:79], v[78:79], off offset:2112
	s_min_i32 s8, s14, 63
	s_xor_b32 s9, s8, 63
	s_and_b64 s[4:5], s[0:1], exec
	s_cselect_b32 s4, s8, s9
	s_or_b32 s4, s4, s11
	s_lshl_b32 s17, s4, 6
	s_lshl_b32 s4, s4, 3
	s_or_b32 s4, s4, s10
	s_ashr_i32 s5, s4, 31
	s_lshl_b64 s[4:5], s[4:5], 1
	s_or_b64 s[4:5], s[4:5], s[68:69]
	s_lshl_b64 s[8:9], s[4:5], 14
	v_lshl_add_u64 v[56:57], v[164:165], 0, s[8:9]
	v_add_u32_e32 v36, s17, v190
	s_lshl_b64 s[8:9], s[4:5], 7
	v_ashrrev_i32_e32 v37, 31, v36
	v_lshl_add_u64 v[64:65], s[8:9], 0, v[128:129]
	v_lshlrev_b64 v[36:37], 11, v[36:37]
	v_lshlrev_b64 v[64:65], 7, v[64:65]
	v_lshl_add_u64 v[60:61], v[166:167], 0, v[36:37]
	v_lshl_add_u64 v[64:65], v[134:135], 0, v[64:65]
	global_load_dwordx4 v[32:35], v[56:57], off
	global_load_dwordx4 v[36:39], v[60:61], off
	global_load_dwordx4 v[40:43], v[56:57], off offset:64
	global_load_dwordx4 v[44:47], v[60:61], off offset:64
	global_load_dwordx4 v[52:55], v[56:57], off offset:128
	global_load_dwordx4 v[48:51], v[60:61], off offset:128
	s_nop 0
	global_load_dwordx4 v[56:59], v[56:57], off offset:192
	s_nop 0
	global_load_dwordx4 v[60:63], v[60:61], off offset:192
	s_lshl_b64 s[4:5], s[4:5], 8
	global_load_dwordx2 v[168:169], v[64:65], off
	v_lshl_add_u64 v[64:65], v[136:137], 0, s[8:9]
	v_lshlrev_b64 v[64:65], 7, v[64:65]
	v_lshl_add_u64 v[64:65], v[134:135], 0, v[64:65]
	global_load_dwordx2 v[170:171], v[64:65], off
	v_lshl_add_u64 v[64:65], v[138:139], 0, s[8:9]
	v_lshlrev_b64 v[64:65], 7, v[64:65]
	v_lshl_add_u64 v[64:65], v[134:135], 0, v[64:65]
	global_load_dwordx2 v[172:173], v[64:65], off
	v_lshl_add_u64 v[64:65], v[140:141], 0, s[8:9]
	v_lshlrev_b64 v[64:65], 7, v[64:65]
	s_add_u32 s4, s37, s4
	v_lshl_add_u64 v[64:65], v[134:135], 0, v[64:65]
	s_addc_u32 s5, s77, s5
	global_load_dwordx2 v[174:175], v[64:65], off
	v_lshl_add_u64 v[64:65], v[132:133], 2, s[4:5]
	global_load_dwordx4 v[64:67], v[64:65], off
	s_nop 0
	global_load_dword v157, v129, s[4:5] offset:252
	s_waitcnt lgkmcnt(0)
	s_barrier
	s_cmp_eq_u32 s14, 1
	s_cbranch_scc1 .LBB0_838
	s_ashr_i32 s5, s18, 31
	s_add_u32 s4, s16, s18
	ds_read_b128 v[184:187], v200
	ds_read_b128 v[212:215], v199
	s_addc_u32 s5, 0, s5
	v_lshl_add_u64 v[188:189], s[4:5], 0, v[154:155]
	v_lshlrev_b64 v[188:189], 11, v[188:189]
	v_lshl_add_u64 v[188:189], v[146:147], 0, v[188:189]
	s_waitcnt lgkmcnt(1)
	global_store_dwordx4 v[188:189], v[184:187], off
	s_nop 1
	v_lshl_add_u64 v[184:185], s[4:5], 0, v[152:153]
	v_lshlrev_b64 v[184:185], 11, v[184:185]
	v_lshl_add_u64 v[184:185], v[146:147], 0, v[184:185]
	s_waitcnt lgkmcnt(0)
	global_store_dwordx4 v[184:185], v[212:215], off

.LBB0_854:
	v_mul_f32_e32 v68, 0x3fb8aa3b, v68
	v_exp_f32_e32 v188, v68
	v_mul_f32_e32 v68, 0x3fb8aa3b, v69
	v_exp_f32_e32 v189, v68
	v_mul_f32_e32 v68, 0x3fb8aa3b, v70
	v_exp_f32_e32 v240, v68
	v_mul_f32_e32 v68, 0x3fb8aa3b, v71
	v_exp_f32_e32 v241, v68
	s_waitcnt lgkmcnt(0)
	s_barrier
	v_pk_mul_f32 v[92:93], v[188:189], v[104:105]
	ds_read_b128 v[68:71], v210 offset:17408
	ds_read_b128 v[120:123], v210 offset:17472
	ds_read_b128 v[176:179], v210 offset:19712
	ds_read_b128 v[180:183], v210 offset:19776
	ds_read_b128 v[184:187], v210 offset:22016
	ds_read_b128 v[212:215], v210 offset:22080
	ds_read_b128 v[216:219], v210 offset:24320
	ds_read_b128 v[220:223], v210 offset:24384
	ds_read_b128 v[224:227], v210 offset:26624
	ds_read_b128 v[228:231], v210 offset:26688
	ds_read_b128 v[232:235], v210 offset:28928
	ds_read_b128 v[236:239], v210 offset:28992
	ds_read_b128 v[112:115], v210 offset:31232
	ds_read_b128 v[108:111], v210 offset:31296
	v_pk_mul_f32 v[94:95], v[240:241], v[106:107]
	v_pk_mul_f32 v[102:103], v[240:241], v[102:103]
	v_pk_mul_f32 v[100:101], v[188:189], v[100:101]
	s_waitcnt vmcnt(19) lgkmcnt(13)
	v_mfma_f32_16x16x32_bf16 v[104:107], v[124:127], v[68:71], v[92:95]
	s_nop 2
	ds_read_b128 v[92:95], v210 offset:33536
	ds_read_b128 v[68:71], v210 offset:33600
	v_pk_mul_f32 v[98:99], v[240:241], v[98:99]
	s_waitcnt vmcnt(16) lgkmcnt(14)
	v_mfma_f32_16x16x32_bf16 v[104:107], v[116:119], v[120:123], v[104:107]
	v_mul_f32_e64 v96, v188, v96
	v_mul_f32_e64 v97, v189, v97
	v_pk_mul_f32 v[90:91], v[240:241], v[90:91]
	v_pk_mul_f32 v[88:89], v[188:189], v[88:89]
	s_waitcnt lgkmcnt(13)
	v_mfma_f32_16x16x32_bf16 v[100:103], v[124:127], v[176:179], v[100:103]
	s_add_i32 s14, s14, 1
	s_nop 0
	v_bfe_u32 v120, v104, 16, 1
	v_add3_u32 v104, v104, v120, s12
	ds_write_b16_d16_hi v156, v104 offset:35840
	v_bfe_u32 v104, v105, 16, 1
	v_add3_u32 v104, v105, v104, s12
	ds_write_b16_d16_hi v158, v104 offset:35840
	v_bfe_u32 v104, v106, 16, 1
	s_waitcnt lgkmcnt(14)
	v_mfma_f32_16x16x32_bf16 v[100:103], v[116:119], v[180:183], v[100:103]
	v_add3_u32 v104, v106, v104, s12
	ds_write_b16_d16_hi v160, v104 offset:35840
	v_bfe_u32 v104, v107, 16, 1
	v_add3_u32 v104, v107, v104, s12
	ds_write_b16_d16_hi v162, v104 offset:35840
	s_nop 2
	v_bfe_u32 v104, v100, 16, 1
	s_waitcnt lgkmcnt(14)
	v_mfma_f32_16x16x32_bf16 v[96:99], v[124:127], v[184:187], v[96:99]
	v_add3_u32 v100, v100, v104, s12
	ds_write_b16_d16_hi v156, v100 offset:35872
	v_bfe_u32 v100, v101, 16, 1
	v_add3_u32 v100, v101, v100, s12
	ds_write_b16_d16_hi v158, v100 offset:35872
	v_bfe_u32 v100, v102, 16, 1
	v_mfma_f32_16x16x32_bf16 v[96:99], v[116:119], v[212:215], v[96:99]
	v_add3_u32 v100, v102, v100, s12
	ds_write_b16_d16_hi v160, v100 offset:35872
	v_bfe_u32 v100, v103, 16, 1
	v_add3_u32 v100, v103, v100, s12
	ds_write_b16_d16_hi v162, v100 offset:35872
	s_nop 2
	v_bfe_u32 v100, v96, 16, 1
	v_add3_u32 v96, v96, v100, s12
	ds_write_b16_d16_hi v156, v96 offset:35904
	v_bfe_u32 v96, v97, 16, 1
	v_add3_u32 v96, v97, v96, s12
	s_waitcnt lgkmcnt(14)
	v_mfma_f32_16x16x32_bf16 v[88:91], v[124:127], v[216:219], v[88:91]
	ds_write_b16_d16_hi v158, v96 offset:35904
	v_bfe_u32 v96, v98, 16, 1
	v_add3_u32 v97, v98, v96, s12
	v_mul_f32_e32 v96, 0x3fb8aa3b, v211
	v_exp_f32_e32 v96, v96
	v_mfma_f32_16x16x32_bf16 v[88:91], v[116:119], v[220:223], v[88:91]
	ds_write_b16_d16_hi v160, v97 offset:35904
	v_bfe_u32 v97, v99, 16, 1
	v_pk_mul_f32 v[2:3], v[2:3], v[96:97] op_sel_hi:[1,0]
	v_pk_mul_f32 v[0:1], v[0:1], v[96:97] op_sel_hi:[1,0]
	v_add3_u32 v97, v99, v97, s12
	ds_write_b16_d16_hi v162, v97 offset:35904
	s_nop 1
	v_bfe_u32 v97, v88, 16, 1
	v_pk_mul_f32 v[18:19], v[18:19], v[96:97] op_sel_hi:[1,0]
	v_pk_mul_f32 v[16:17], v[16:17], v[96:97] op_sel_hi:[1,0]
	v_mfma_f32_16x16x32_bf16 v[0:3], v[80:83], v[224:227], v[0:3]
	v_mul_f32_e64 v6, v6, v96
	v_mul_f32_e64 v7, v7, v96
	v_pk_mul_f32 v[4:5], v[4:5], v[96:97] op_sel_hi:[1,0]
	v_pk_mul_f32 v[10:11], v[10:11], v[96:97] op_sel_hi:[1,0]
	v_pk_mul_f32 v[8:9], v[8:9], v[96:97] op_sel_hi:[1,0]
	v_pk_mul_f32 v[14:15], v[14:15], v[96:97] op_sel_hi:[1,0]
	v_pk_mul_f32 v[12:13], v[12:13], v[96:97] op_sel_hi:[1,0]
	v_mfma_f32_16x16x32_bf16 v[16:19], v[72:75], v[224:227], v[16:19]
	v_mul_f32_e64 v22, v22, v96
	v_mul_f32_e64 v23, v23, v96
	v_pk_mul_f32 v[20:21], v[20:21], v[96:97] op_sel_hi:[1,0]
	v_pk_mul_f32 v[26:27], v[26:27], v[96:97] op_sel_hi:[1,0]
	v_pk_mul_f32 v[24:25], v[24:25], v[96:97] op_sel_hi:[1,0]
	v_pk_mul_f32 v[30:31], v[30:31], v[96:97] op_sel_hi:[1,0]
	v_pk_mul_f32 v[28:29], v[28:29], v[96:97] op_sel_hi:[1,0]
	v_add3_u32 v88, v88, v97, s12
	v_mfma_f32_16x16x32_bf16 v[4:7], v[80:83], v[232:235], v[4:7]
	ds_write_b16_d16_hi v156, v88 offset:35936
	v_bfe_u32 v88, v89, 16, 1
	v_add3_u32 v88, v89, v88, s12
	s_waitcnt lgkmcnt(14)
	v_mfma_f32_16x16x32_bf16 v[8:11], v[80:83], v[112:115], v[8:11]
	ds_write_b16_d16_hi v158, v88 offset:35936
	v_bfe_u32 v88, v90, 16, 1
	v_add3_u32 v88, v90, v88, s12
	v_mfma_f32_16x16x32_bf16 v[12:15], v[80:83], v[92:95], v[12:15]
	ds_write_b16_d16_hi v160, v88 offset:35936
	v_bfe_u32 v88, v91, 16, 1
	v_add3_u32 v80, v91, v88, s12
	v_mfma_f32_16x16x32_bf16 v[20:23], v[72:75], v[232:235], v[20:23]
	ds_write_b16_d16_hi v162, v80 offset:35936
	s_cmpk_lg_i32 s14, 0x41
	v_mfma_f32_16x16x32_bf16 v[24:27], v[72:75], v[112:115], v[24:27]
	v_mfma_f32_16x16x32_bf16 v[28:31], v[72:75], v[92:95], v[28:31]
	s_waitcnt vmcnt(15)
	v_mfma_f32_16x16x32_bf16 v[0:3], v[84:87], v[228:231], v[0:3]
	s_waitcnt vmcnt(14)
	v_mfma_f32_16x16x32_bf16 v[16:19], v[76:79], v[228:231], v[16:19]
	v_mfma_f32_16x16x32_bf16 v[4:7], v[84:87], v[236:239], v[4:7]
	s_nop 4
	v_cvt_pk_bf16_f32 v81, v2, v3
	v_cvt_pk_bf16_f32 v80, v0, v1
	v_cvt_pk_bf16_f32 v89, v18, v19
	v_mfma_f32_16x16x32_bf16 v[8:11], v[84:87], v[108:111], v[8:11]
	v_cvt_pk_bf16_f32 v88, v16, v17
	v_cvt_pk_bf16_f32 v83, v6, v7
	v_cvt_pk_bf16_f32 v82, v4, v5
	s_waitcnt lgkmcnt(14)
	v_mfma_f32_16x16x32_bf16 v[12:15], v[84:87], v[68:71], v[12:15]
	ds_write2_b64 v191, v[80:81], v[88:89] offset1:4
	s_nop 1
	v_cvt_pk_bf16_f32 v85, v10, v11
	v_cvt_pk_bf16_f32 v84, v8, v9
	v_mfma_f32_16x16x32_bf16 v[20:23], v[76:79], v[236:239], v[20:23]
	v_mfma_f32_16x16x32_bf16 v[24:27], v[76:79], v[108:111], v[24:27]
	s_nop 0
	v_cvt_pk_bf16_f32 v87, v14, v15
	v_cvt_pk_bf16_f32 v86, v12, v13
	s_nop 3
	v_cvt_pk_bf16_f32 v81, v22, v23
	v_mfma_f32_16x16x32_bf16 v[28:31], v[76:79], v[68:71], v[28:31]
	v_cvt_pk_bf16_f32 v80, v20, v21
	v_cvt_pk_bf16_f32 v73, v26, v27
	v_cvt_pk_bf16_f32 v72, v24, v25
	ds_write2_b64 v196, v[82:83], v[80:81] offset0:32 offset1:36
	ds_write2_b64 v197, v[84:85], v[72:73] offset0:64 offset1:68
	s_nop 2
	v_cvt_pk_bf16_f32 v69, v30, v31
	v_cvt_pk_bf16_f32 v68, v28, v29
	ds_write2_b64 v198, v[86:87], v[68:69] offset0:96 offset1:100
	s_waitcnt vmcnt(0)
	s_cbranch_scc0 .LBB0_856
	v_mov_b64_e32 v[114:115], v[34:35]
	v_mov_b64_e32 v[106:107], v[42:43]
	v_mov_b64_e32 v[98:99], v[54:55]
	v_mov_b64_e32 v[90:91], v[58:59]
	v_mov_b64_e32 v[122:123], v[38:39]
	v_mov_b64_e32 v[110:111], v[46:47]
	v_mov_b64_e32 v[102:103], v[50:51]
	v_mov_b64_e32 v[94:95], v[62:63]
	v_mov_b64_e32 v[70:71], v[66:67]
	s_mov_b32 s18, s15
	v_mov_b64_e32 v[112:113], v[32:33]
	v_mov_b64_e32 v[104:105], v[40:41]
	v_mov_b64_e32 v[96:97], v[52:53]
	v_mov_b64_e32 v[88:89], v[56:57]
	v_mov_b64_e32 v[120:121], v[36:37]
	v_mov_b64_e32 v[108:109], v[44:45]
	v_mov_b64_e32 v[100:101], v[48:49]
	v_mov_b64_e32 v[92:93], v[60:61]
	v_mov_b64_e32 v[182:183], v[168:169]
	v_mov_b64_e32 v[180:181], v[170:171]
	v_mov_b64_e32 v[178:179], v[172:173]
	v_mov_b64_e32 v[176:177], v[174:175]
	v_mov_b64_e32 v[68:69], v[64:65]
	v_mov_b32_e32 v211, v157
	s_mov_b32 s15, s17
	s_branch .LBB0_836
